# phase 7: hand-written EpiOut epilogue (saddr loads/stores with immediate row offsets, x loads double-buffered two row groups ahead)
# speedup vs baseline: 1.0144x; 1.0005x over previous
.LBB0_1382:
	s_waitcnt vmcnt(0)
	v_and_b32_e32 v196, 0xc0, v208
	v_and_b32_e32 v197, 31, v208
	v_or3_b32 v196, v196, s30, v197
	s_lshr_b32 s14, s29, 13
	s_mul_i32 s14, s14, 0x3000
	s_add_u32 s14, s14, 0x2000
	v_lshl_add_u32 v197, v196, 2, s14
	global_load_dword v198, v197, s[94:95]
	global_load_dword v199, v197, s[94:95] offset:128
	v_lshrrev_b32_e32 v200, 8, v208
	v_bfe_u32 v201, v208, 5, 1
	v_lshlrev_b32_e32 v200, 7, v200
	v_lshl_or_b32 v200, v201, 2, v200
	v_add_u32_e32 v200, s29, v200
	v_lshlrev_b32_e32 v201, 12, v200
	v_lshl_add_u32 v201, v196, 2, v201
	v_lshlrev_b32_e32 v202, 11, v200
	v_lshl_add_u32 v202, v196, 1, v202
	v_add_u32_e32 v203, 0x1000, v201
	v_add_u32_e32 v204, 0x2000, v203
	global_load_dword v128, v203, s[60:61] offset:-4096
	global_load_dword v129, v203, s[60:61] offset:0
	global_load_dword v130, v204, s[60:61] offset:-4096
	global_load_dword v131, v204, s[60:61] offset:0
	global_load_dword v132, v203, s[60:61] offset:-3968
	global_load_dword v133, v203, s[60:61] offset:128
	global_load_dword v134, v204, s[60:61] offset:-3968
	global_load_dword v135, v204, s[60:61] offset:128
	v_add_u32_e32 v205, 0x9000, v201
	v_add_u32_e32 v206, 0x2000, v205
	global_load_dword v136, v205, s[60:61] offset:-4096
	global_load_dword v137, v205, s[60:61] offset:0
	global_load_dword v138, v206, s[60:61] offset:-4096
	global_load_dword v139, v206, s[60:61] offset:0
	global_load_dword v140, v205, s[60:61] offset:-3968
	global_load_dword v141, v205, s[60:61] offset:128
	global_load_dword v142, v206, s[60:61] offset:-3968
	global_load_dword v143, v206, s[60:61] offset:128
	s_waitcnt vmcnt(8)
	v_fmac_f32_e32 v128, v198, v112
	v_fmac_f32_e32 v129, v198, v113
	v_fmac_f32_e32 v130, v198, v114
	v_fmac_f32_e32 v131, v198, v115
	v_fmac_f32_e32 v132, v199, v96
	v_fmac_f32_e32 v133, v199, v97
	v_fmac_f32_e32 v134, v199, v98
	v_fmac_f32_e32 v135, v199, v99
	v_cvt_pk_bf16_f32 v144, v128, v129
	v_cvt_pk_bf16_f32 v145, v130, v131
	v_cvt_pk_bf16_f32 v146, v132, v133
	v_cvt_pk_bf16_f32 v147, v134, v135
	v_add_u32_e32 v207, 0x1000, v202
	global_store_short v207, v144, s[8:9] offset:-4096
	global_store_short_d16_hi v207, v144, s[8:9] offset:-2048
	global_store_short v207, v145, s[8:9] offset:0
	global_store_short_d16_hi v207, v145, s[8:9] offset:2048
	global_store_short v207, v146, s[8:9] offset:-4032
	global_store_short_d16_hi v207, v146, s[8:9] offset:-1984
	global_store_short v207, v147, s[8:9] offset:64
	global_store_short_d16_hi v207, v147, s[8:9] offset:2112
	v_add_u32_e32 v203, 0x11000, v201
	v_add_u32_e32 v204, 0x2000, v203
	global_load_dword v128, v203, s[60:61] offset:-4096
	global_load_dword v129, v203, s[60:61] offset:0
	global_load_dword v130, v204, s[60:61] offset:-4096
	global_load_dword v131, v204, s[60:61] offset:0
	global_load_dword v132, v203, s[60:61] offset:-3968
	global_load_dword v133, v203, s[60:61] offset:128
	global_load_dword v134, v204, s[60:61] offset:-3968
	global_load_dword v135, v204, s[60:61] offset:128
	s_waitcnt vmcnt(16)
	v_fmac_f32_e32 v136, v198, v116
	v_fmac_f32_e32 v137, v198, v117
	v_fmac_f32_e32 v138, v198, v118
	v_fmac_f32_e32 v139, v198, v119
	v_fmac_f32_e32 v140, v199, v100
	v_fmac_f32_e32 v141, v199, v101
	v_fmac_f32_e32 v142, v199, v102
	v_fmac_f32_e32 v143, v199, v103
	v_cvt_pk_bf16_f32 v148, v136, v137
	v_cvt_pk_bf16_f32 v149, v138, v139
	v_cvt_pk_bf16_f32 v150, v140, v141
	v_cvt_pk_bf16_f32 v151, v142, v143
	v_add_u32_e32 v207, 0x5000, v202
	global_store_short v207, v148, s[8:9] offset:-4096
	global_store_short_d16_hi v207, v148, s[8:9] offset:-2048
	global_store_short v207, v149, s[8:9] offset:0
	global_store_short_d16_hi v207, v149, s[8:9] offset:2048
	global_store_short v207, v150, s[8:9] offset:-4032
	global_store_short_d16_hi v207, v150, s[8:9] offset:-1984
	global_store_short v207, v151, s[8:9] offset:64
	global_store_short_d16_hi v207, v151, s[8:9] offset:2112
	v_add_u32_e32 v205, 0x19000, v201
	v_add_u32_e32 v206, 0x2000, v205
	global_load_dword v136, v205, s[60:61] offset:-4096
	global_load_dword v137, v205, s[60:61] offset:0
	global_load_dword v138, v206, s[60:61] offset:-4096
	global_load_dword v139, v206, s[60:61] offset:0
	global_load_dword v140, v205, s[60:61] offset:-3968
	global_load_dword v141, v205, s[60:61] offset:128
	global_load_dword v142, v206, s[60:61] offset:-3968
	global_load_dword v143, v206, s[60:61] offset:128
	s_waitcnt vmcnt(16)
	v_fmac_f32_e32 v128, v198, v120
	v_fmac_f32_e32 v129, v198, v121
	v_fmac_f32_e32 v130, v198, v122
	v_fmac_f32_e32 v131, v198, v123
	v_fmac_f32_e32 v132, v199, v104
	v_fmac_f32_e32 v133, v199, v105
	v_fmac_f32_e32 v134, v199, v106
	v_fmac_f32_e32 v135, v199, v107
	v_cvt_pk_bf16_f32 v144, v128, v129
	v_cvt_pk_bf16_f32 v145, v130, v131
	v_cvt_pk_bf16_f32 v146, v132, v133
	v_cvt_pk_bf16_f32 v147, v134, v135
	v_add_u32_e32 v207, 0x9000, v202
	global_store_short v207, v144, s[8:9] offset:-4096
	global_store_short_d16_hi v207, v144, s[8:9] offset:-2048
	global_store_short v207, v145, s[8:9] offset:0
	global_store_short_d16_hi v207, v145, s[8:9] offset:2048
	global_store_short v207, v146, s[8:9] offset:-4032
	global_store_short_d16_hi v207, v146, s[8:9] offset:-1984
	global_store_short v207, v147, s[8:9] offset:64
	global_store_short_d16_hi v207, v147, s[8:9] offset:2112
	v_add_u32_e32 v203, 0x21000, v201
	v_add_u32_e32 v204, 0x2000, v203
	global_load_dword v128, v203, s[60:61] offset:-4096
	global_load_dword v129, v203, s[60:61] offset:0
	global_load_dword v130, v204, s[60:61] offset:-4096
	global_load_dword v131, v204, s[60:61] offset:0
	global_load_dword v132, v203, s[60:61] offset:-3968
	global_load_dword v133, v203, s[60:61] offset:128
	global_load_dword v134, v204, s[60:61] offset:-3968
	global_load_dword v135, v204, s[60:61] offset:128
	s_waitcnt vmcnt(16)
	v_fmac_f32_e32 v136, v198, v124
	v_fmac_f32_e32 v137, v198, v125
	v_fmac_f32_e32 v138, v198, v126
	v_fmac_f32_e32 v139, v198, v127
	v_fmac_f32_e32 v140, v199, v108
	v_fmac_f32_e32 v141, v199, v109
	v_fmac_f32_e32 v142, v199, v110
	v_fmac_f32_e32 v143, v199, v111
	v_cvt_pk_bf16_f32 v148, v136, v137
	v_cvt_pk_bf16_f32 v149, v138, v139
	v_cvt_pk_bf16_f32 v150, v140, v141
	v_cvt_pk_bf16_f32 v151, v142, v143
	v_add_u32_e32 v207, 0xd000, v202
	global_store_short v207, v148, s[8:9] offset:-4096
	global_store_short_d16_hi v207, v148, s[8:9] offset:-2048
	global_store_short v207, v149, s[8:9] offset:0
	global_store_short_d16_hi v207, v149, s[8:9] offset:2048
	global_store_short v207, v150, s[8:9] offset:-4032
	global_store_short_d16_hi v207, v150, s[8:9] offset:-1984
	global_store_short v207, v151, s[8:9] offset:64
	global_store_short_d16_hi v207, v151, s[8:9] offset:2112
	v_add_u32_e32 v205, 0x29000, v201
	v_add_u32_e32 v206, 0x2000, v205
	global_load_dword v136, v205, s[60:61] offset:-4096
	global_load_dword v137, v205, s[60:61] offset:0
	global_load_dword v138, v206, s[60:61] offset:-4096
	global_load_dword v139, v206, s[60:61] offset:0
	global_load_dword v140, v205, s[60:61] offset:-3968
	global_load_dword v141, v205, s[60:61] offset:128
	global_load_dword v142, v206, s[60:61] offset:-3968
	global_load_dword v143, v206, s[60:61] offset:128
	s_waitcnt vmcnt(16)
	v_fmac_f32_e32 v128, v198, v80
	v_fmac_f32_e32 v129, v198, v81
	v_fmac_f32_e32 v130, v198, v82
	v_fmac_f32_e32 v131, v198, v83
	v_fmac_f32_e32 v132, v199, v64
	v_fmac_f32_e32 v133, v199, v65
	v_fmac_f32_e32 v134, v199, v66
	v_fmac_f32_e32 v135, v199, v67
	v_cvt_pk_bf16_f32 v144, v128, v129
	v_cvt_pk_bf16_f32 v145, v130, v131
	v_cvt_pk_bf16_f32 v146, v132, v133
	v_cvt_pk_bf16_f32 v147, v134, v135
	v_add_u32_e32 v207, 0x11000, v202
	global_store_short v207, v144, s[8:9] offset:-4096
	global_store_short_d16_hi v207, v144, s[8:9] offset:-2048
	global_store_short v207, v145, s[8:9] offset:0
	global_store_short_d16_hi v207, v145, s[8:9] offset:2048
	global_store_short v207, v146, s[8:9] offset:-4032
	global_store_short_d16_hi v207, v146, s[8:9] offset:-1984
	global_store_short v207, v147, s[8:9] offset:64
	global_store_short_d16_hi v207, v147, s[8:9] offset:2112
	v_add_u32_e32 v203, 0x31000, v201
	v_add_u32_e32 v204, 0x2000, v203
	global_load_dword v128, v203, s[60:61] offset:-4096
	global_load_dword v129, v203, s[60:61] offset:0
	global_load_dword v130, v204, s[60:61] offset:-4096
	global_load_dword v131, v204, s[60:61] offset:0
	global_load_dword v132, v203, s[60:61] offset:-3968
	global_load_dword v133, v203, s[60:61] offset:128
	global_load_dword v134, v204, s[60:61] offset:-3968
	global_load_dword v135, v204, s[60:61] offset:128
	s_waitcnt vmcnt(16)
	v_fmac_f32_e32 v136, v198, v84
	v_fmac_f32_e32 v137, v198, v85
	v_fmac_f32_e32 v138, v198, v86
	v_fmac_f32_e32 v139, v198, v87
	v_fmac_f32_e32 v140, v199, v68
	v_fmac_f32_e32 v141, v199, v69
	v_fmac_f32_e32 v142, v199, v70
	v_fmac_f32_e32 v143, v199, v71
	v_cvt_pk_bf16_f32 v148, v136, v137
	v_cvt_pk_bf16_f32 v149, v138, v139
	v_cvt_pk_bf16_f32 v150, v140, v141
	v_cvt_pk_bf16_f32 v151, v142, v143
	v_add_u32_e32 v207, 0x15000, v202
	global_store_short v207, v148, s[8:9] offset:-4096
	global_store_short_d16_hi v207, v148, s[8:9] offset:-2048
	global_store_short v207, v149, s[8:9] offset:0
	global_store_short_d16_hi v207, v149, s[8:9] offset:2048
	global_store_short v207, v150, s[8:9] offset:-4032
	global_store_short_d16_hi v207, v150, s[8:9] offset:-1984
	global_store_short v207, v151, s[8:9] offset:64
	global_store_short_d16_hi v207, v151, s[8:9] offset:2112
	v_add_u32_e32 v205, 0x39000, v201
	v_add_u32_e32 v206, 0x2000, v205
	global_load_dword v136, v205, s[60:61] offset:-4096
	global_load_dword v137, v205, s[60:61] offset:0
	global_load_dword v138, v206, s[60:61] offset:-4096
	global_load_dword v139, v206, s[60:61] offset:0
	global_load_dword v140, v205, s[60:61] offset:-3968
	global_load_dword v141, v205, s[60:61] offset:128
	global_load_dword v142, v206, s[60:61] offset:-3968
	global_load_dword v143, v206, s[60:61] offset:128
	s_waitcnt vmcnt(16)
	v_fmac_f32_e32 v128, v198, v88
	v_fmac_f32_e32 v129, v198, v89
	v_fmac_f32_e32 v130, v198, v90
	v_fmac_f32_e32 v131, v198, v91
	v_fmac_f32_e32 v132, v199, v72
	v_fmac_f32_e32 v133, v199, v73
	v_fmac_f32_e32 v134, v199, v74
	v_fmac_f32_e32 v135, v199, v75
	v_cvt_pk_bf16_f32 v144, v128, v129
	v_cvt_pk_bf16_f32 v145, v130, v131
	v_cvt_pk_bf16_f32 v146, v132, v133
	v_cvt_pk_bf16_f32 v147, v134, v135
	v_add_u32_e32 v207, 0x19000, v202
	global_store_short v207, v144, s[8:9] offset:-4096
	global_store_short_d16_hi v207, v144, s[8:9] offset:-2048
	global_store_short v207, v145, s[8:9] offset:0
	global_store_short_d16_hi v207, v145, s[8:9] offset:2048
	global_store_short v207, v146, s[8:9] offset:-4032
	global_store_short_d16_hi v207, v146, s[8:9] offset:-1984
	global_store_short v207, v147, s[8:9] offset:64
	global_store_short_d16_hi v207, v147, s[8:9] offset:2112
	v_add_u32_e32 v203, 0x41000, v201
	v_add_u32_e32 v204, 0x2000, v203
	global_load_dword v128, v203, s[60:61] offset:-4096
	global_load_dword v129, v203, s[60:61] offset:0
	global_load_dword v130, v204, s[60:61] offset:-4096
	global_load_dword v131, v204, s[60:61] offset:0
	global_load_dword v132, v203, s[60:61] offset:-3968
	global_load_dword v133, v203, s[60:61] offset:128
	global_load_dword v134, v204, s[60:61] offset:-3968
	global_load_dword v135, v204, s[60:61] offset:128
	s_waitcnt vmcnt(16)
	v_fmac_f32_e32 v136, v198, v92
	v_fmac_f32_e32 v137, v198, v93
	v_fmac_f32_e32 v138, v198, v94
	v_fmac_f32_e32 v139, v198, v95
	v_fmac_f32_e32 v140, v199, v76
	v_fmac_f32_e32 v141, v199, v77
	v_fmac_f32_e32 v142, v199, v78
	v_fmac_f32_e32 v143, v199, v79
	v_cvt_pk_bf16_f32 v148, v136, v137
	v_cvt_pk_bf16_f32 v149, v138, v139
	v_cvt_pk_bf16_f32 v150, v140, v141
	v_cvt_pk_bf16_f32 v151, v142, v143
	v_add_u32_e32 v207, 0x1d000, v202
	global_store_short v207, v148, s[8:9] offset:-4096
	global_store_short_d16_hi v207, v148, s[8:9] offset:-2048
	global_store_short v207, v149, s[8:9] offset:0
	global_store_short_d16_hi v207, v149, s[8:9] offset:2048
	global_store_short v207, v150, s[8:9] offset:-4032
	global_store_short_d16_hi v207, v150, s[8:9] offset:-1984
	global_store_short v207, v151, s[8:9] offset:64
	global_store_short_d16_hi v207, v151, s[8:9] offset:2112
	v_add_u32_e32 v205, 0x49000, v201
	v_add_u32_e32 v206, 0x2000, v205
	global_load_dword v136, v205, s[60:61] offset:-4096
	global_load_dword v137, v205, s[60:61] offset:0
	global_load_dword v138, v206, s[60:61] offset:-4096
	global_load_dword v139, v206, s[60:61] offset:0
	global_load_dword v140, v205, s[60:61] offset:-3968
	global_load_dword v141, v205, s[60:61] offset:128
	global_load_dword v142, v206, s[60:61] offset:-3968
	global_load_dword v143, v206, s[60:61] offset:128
	s_waitcnt vmcnt(16)
	v_fmac_f32_e32 v128, v198, v48
	v_fmac_f32_e32 v129, v198, v49
	v_fmac_f32_e32 v130, v198, v50
	v_fmac_f32_e32 v131, v198, v51
	v_fmac_f32_e32 v132, v199, v32
	v_fmac_f32_e32 v133, v199, v33
	v_fmac_f32_e32 v134, v199, v34
	v_fmac_f32_e32 v135, v199, v35
	v_cvt_pk_bf16_f32 v144, v128, v129
	v_cvt_pk_bf16_f32 v145, v130, v131
	v_cvt_pk_bf16_f32 v146, v132, v133
	v_cvt_pk_bf16_f32 v147, v134, v135
	v_add_u32_e32 v207, 0x21000, v202
	global_store_short v207, v144, s[8:9] offset:-4096
	global_store_short_d16_hi v207, v144, s[8:9] offset:-2048
	global_store_short v207, v145, s[8:9] offset:0
	global_store_short_d16_hi v207, v145, s[8:9] offset:2048
	global_store_short v207, v146, s[8:9] offset:-4032
	global_store_short_d16_hi v207, v146, s[8:9] offset:-1984
	global_store_short v207, v147, s[8:9] offset:64
	global_store_short_d16_hi v207, v147, s[8:9] offset:2112
	v_add_u32_e32 v203, 0x51000, v201
	v_add_u32_e32 v204, 0x2000, v203
	global_load_dword v128, v203, s[60:61] offset:-4096
	global_load_dword v129, v203, s[60:61] offset:0
	global_load_dword v130, v204, s[60:61] offset:-4096
	global_load_dword v131, v204, s[60:61] offset:0
	global_load_dword v132, v203, s[60:61] offset:-3968
	global_load_dword v133, v203, s[60:61] offset:128
	global_load_dword v134, v204, s[60:61] offset:-3968
	global_load_dword v135, v204, s[60:61] offset:128
	s_waitcnt vmcnt(16)
	v_fmac_f32_e32 v136, v198, v52
	v_fmac_f32_e32 v137, v198, v53
	v_fmac_f32_e32 v138, v198, v54
	v_fmac_f32_e32 v139, v198, v55
	v_fmac_f32_e32 v140, v199, v36
	v_fmac_f32_e32 v141, v199, v37
	v_fmac_f32_e32 v142, v199, v38
	v_fmac_f32_e32 v143, v199, v39
	v_cvt_pk_bf16_f32 v148, v136, v137
	v_cvt_pk_bf16_f32 v149, v138, v139
	v_cvt_pk_bf16_f32 v150, v140, v141
	v_cvt_pk_bf16_f32 v151, v142, v143
	v_add_u32_e32 v207, 0x25000, v202
	global_store_short v207, v148, s[8:9] offset:-4096
	global_store_short_d16_hi v207, v148, s[8:9] offset:-2048
	global_store_short v207, v149, s[8:9] offset:0
	global_store_short_d16_hi v207, v149, s[8:9] offset:2048
	global_store_short v207, v150, s[8:9] offset:-4032
	global_store_short_d16_hi v207, v150, s[8:9] offset:-1984
	global_store_short v207, v151, s[8:9] offset:64
	global_store_short_d16_hi v207, v151, s[8:9] offset:2112
	v_add_u32_e32 v205, 0x59000, v201
	v_add_u32_e32 v206, 0x2000, v205
	global_load_dword v136, v205, s[60:61] offset:-4096
	global_load_dword v137, v205, s[60:61] offset:0
	global_load_dword v138, v206, s[60:61] offset:-4096
	global_load_dword v139, v206, s[60:61] offset:0
	global_load_dword v140, v205, s[60:61] offset:-3968
	global_load_dword v141, v205, s[60:61] offset:128
	global_load_dword v142, v206, s[60:61] offset:-3968
	global_load_dword v143, v206, s[60:61] offset:128
	s_waitcnt vmcnt(16)
	v_fmac_f32_e32 v128, v198, v56
	v_fmac_f32_e32 v129, v198, v57
	v_fmac_f32_e32 v130, v198, v58
	v_fmac_f32_e32 v131, v198, v59
	v_fmac_f32_e32 v132, v199, v40
	v_fmac_f32_e32 v133, v199, v41
	v_fmac_f32_e32 v134, v199, v42
	v_fmac_f32_e32 v135, v199, v43
	v_cvt_pk_bf16_f32 v144, v128, v129
	v_cvt_pk_bf16_f32 v145, v130, v131
	v_cvt_pk_bf16_f32 v146, v132, v133
	v_cvt_pk_bf16_f32 v147, v134, v135
	v_add_u32_e32 v207, 0x29000, v202
	global_store_short v207, v144, s[8:9] offset:-4096
	global_store_short_d16_hi v207, v144, s[8:9] offset:-2048
	global_store_short v207, v145, s[8:9] offset:0
	global_store_short_d16_hi v207, v145, s[8:9] offset:2048
	global_store_short v207, v146, s[8:9] offset:-4032
	global_store_short_d16_hi v207, v146, s[8:9] offset:-1984
	global_store_short v207, v147, s[8:9] offset:64
	global_store_short_d16_hi v207, v147, s[8:9] offset:2112
	v_add_u32_e32 v203, 0x61000, v201
	v_add_u32_e32 v204, 0x2000, v203
	global_load_dword v128, v203, s[60:61] offset:-4096
	global_load_dword v129, v203, s[60:61] offset:0
	global_load_dword v130, v204, s[60:61] offset:-4096
	global_load_dword v131, v204, s[60:61] offset:0
	global_load_dword v132, v203, s[60:61] offset:-3968
	global_load_dword v133, v203, s[60:61] offset:128
	global_load_dword v134, v204, s[60:61] offset:-3968
	global_load_dword v135, v204, s[60:61] offset:128
	s_waitcnt vmcnt(16)
; DI void phase7(const Params& P, unsigned char* lds) {
;     ...
;   for (int t = blockIdx.x; t < 64 * 4; t += gridDim.x) gemm_tile(g, (t >> 2) * BM, (t & 3) * BN, lds, e);
	v_fmac_f32_e32 v136, v198, v60
	v_fmac_f32_e32 v137, v198, v61
	v_fmac_f32_e32 v138, v198, v62
	v_fmac_f32_e32 v139, v198, v63
	v_fmac_f32_e32 v140, v199, v44
	v_fmac_f32_e32 v141, v199, v45
	v_fmac_f32_e32 v142, v199, v46
	v_fmac_f32_e32 v143, v199, v47
	v_cvt_pk_bf16_f32 v148, v136, v137
	v_cvt_pk_bf16_f32 v149, v138, v139
	v_cvt_pk_bf16_f32 v150, v140, v141
	v_cvt_pk_bf16_f32 v151, v142, v143
	v_add_u32_e32 v207, 0x2d000, v202
	global_store_short v207, v148, s[8:9] offset:-4096
	global_store_short_d16_hi v207, v148, s[8:9] offset:-2048
	global_store_short v207, v149, s[8:9] offset:0
	global_store_short_d16_hi v207, v149, s[8:9] offset:2048
	global_store_short v207, v150, s[8:9] offset:-4032
	global_store_short_d16_hi v207, v150, s[8:9] offset:-1984
	global_store_short v207, v151, s[8:9] offset:64
	global_store_short_d16_hi v207, v151, s[8:9] offset:2112
	v_add_u32_e32 v205, 0x69000, v201
	v_add_u32_e32 v206, 0x2000, v205
	global_load_dword v136, v205, s[60:61] offset:-4096
	global_load_dword v137, v205, s[60:61] offset:0
	global_load_dword v138, v206, s[60:61] offset:-4096
	global_load_dword v139, v206, s[60:61] offset:0
	global_load_dword v140, v205, s[60:61] offset:-3968
	global_load_dword v141, v205, s[60:61] offset:128
	global_load_dword v142, v206, s[60:61] offset:-3968
	global_load_dword v143, v206, s[60:61] offset:128
	s_waitcnt vmcnt(16)
	v_fmac_f32_e32 v128, v198, v16
	v_fmac_f32_e32 v129, v198, v17
	v_fmac_f32_e32 v130, v198, v18
	v_fmac_f32_e32 v131, v198, v19
	v_fmac_f32_e32 v132, v199, v0
	v_fmac_f32_e32 v133, v199, v1
	v_fmac_f32_e32 v134, v199, v2
	v_fmac_f32_e32 v135, v199, v3
	v_cvt_pk_bf16_f32 v144, v128, v129
	v_cvt_pk_bf16_f32 v145, v130, v131
	v_cvt_pk_bf16_f32 v146, v132, v133
	v_cvt_pk_bf16_f32 v147, v134, v135
	v_add_u32_e32 v207, 0x31000, v202
	global_store_short v207, v144, s[8:9] offset:-4096
	global_store_short_d16_hi v207, v144, s[8:9] offset:-2048
	global_store_short v207, v145, s[8:9] offset:0
	global_store_short_d16_hi v207, v145, s[8:9] offset:2048
	global_store_short v207, v146, s[8:9] offset:-4032
	global_store_short_d16_hi v207, v146, s[8:9] offset:-1984
	global_store_short v207, v147, s[8:9] offset:64
	global_store_short_d16_hi v207, v147, s[8:9] offset:2112
	v_add_u32_e32 v203, 0x71000, v201
	v_add_u32_e32 v204, 0x2000, v203
	global_load_dword v128, v203, s[60:61] offset:-4096
	global_load_dword v129, v203, s[60:61] offset:0
	global_load_dword v130, v204, s[60:61] offset:-4096
	global_load_dword v131, v204, s[60:61] offset:0
	global_load_dword v132, v203, s[60:61] offset:-3968
	global_load_dword v133, v203, s[60:61] offset:128
	global_load_dword v134, v204, s[60:61] offset:-3968
	global_load_dword v135, v204, s[60:61] offset:128
	s_waitcnt vmcnt(16)
	v_fmac_f32_e32 v136, v198, v20
	v_fmac_f32_e32 v137, v198, v21
	v_fmac_f32_e32 v138, v198, v22
	v_fmac_f32_e32 v139, v198, v23
	v_fmac_f32_e32 v140, v199, v4
	v_fmac_f32_e32 v141, v199, v5
	v_fmac_f32_e32 v142, v199, v6
	v_fmac_f32_e32 v143, v199, v7
	v_cvt_pk_bf16_f32 v148, v136, v137
	v_cvt_pk_bf16_f32 v149, v138, v139
	v_cvt_pk_bf16_f32 v150, v140, v141
	v_cvt_pk_bf16_f32 v151, v142, v143
	v_add_u32_e32 v207, 0x35000, v202
	global_store_short v207, v148, s[8:9] offset:-4096
	global_store_short_d16_hi v207, v148, s[8:9] offset:-2048
	global_store_short v207, v149, s[8:9] offset:0
	global_store_short_d16_hi v207, v149, s[8:9] offset:2048
	global_store_short v207, v150, s[8:9] offset:-4032
	global_store_short_d16_hi v207, v150, s[8:9] offset:-1984
	global_store_short v207, v151, s[8:9] offset:64
	global_store_short_d16_hi v207, v151, s[8:9] offset:2112
	v_add_u32_e32 v205, 0x79000, v201
	v_add_u32_e32 v206, 0x2000, v205
	global_load_dword v136, v205, s[60:61] offset:-4096
	global_load_dword v137, v205, s[60:61] offset:0
	global_load_dword v138, v206, s[60:61] offset:-4096
	global_load_dword v139, v206, s[60:61] offset:0
	global_load_dword v140, v205, s[60:61] offset:-3968
	global_load_dword v141, v205, s[60:61] offset:128
	global_load_dword v142, v206, s[60:61] offset:-3968
	global_load_dword v143, v206, s[60:61] offset:128
	s_waitcnt vmcnt(16)
	v_fmac_f32_e32 v128, v198, v24
	v_fmac_f32_e32 v129, v198, v25
	v_fmac_f32_e32 v130, v198, v26
	v_fmac_f32_e32 v131, v198, v27
	v_fmac_f32_e32 v132, v199, v8
	v_fmac_f32_e32 v133, v199, v9
	v_fmac_f32_e32 v134, v199, v10
	v_fmac_f32_e32 v135, v199, v11
	v_cvt_pk_bf16_f32 v144, v128, v129
	v_cvt_pk_bf16_f32 v145, v130, v131
	v_cvt_pk_bf16_f32 v146, v132, v133
	v_cvt_pk_bf16_f32 v147, v134, v135
	v_add_u32_e32 v207, 0x39000, v202
	global_store_short v207, v144, s[8:9] offset:-4096
	global_store_short_d16_hi v207, v144, s[8:9] offset:-2048
	global_store_short v207, v145, s[8:9] offset:0
	global_store_short_d16_hi v207, v145, s[8:9] offset:2048
	global_store_short v207, v146, s[8:9] offset:-4032
	global_store_short_d16_hi v207, v146, s[8:9] offset:-1984
	global_store_short v207, v147, s[8:9] offset:64
	global_store_short_d16_hi v207, v147, s[8:9] offset:2112
	s_waitcnt vmcnt(8)
	v_fmac_f32_e32 v136, v198, v28
	v_fmac_f32_e32 v137, v198, v29
	v_fmac_f32_e32 v138, v198, v30
	v_fmac_f32_e32 v139, v198, v31
	v_fmac_f32_e32 v140, v199, v12
	v_fmac_f32_e32 v141, v199, v13
	v_fmac_f32_e32 v142, v199, v14
	v_fmac_f32_e32 v143, v199, v15
	v_cvt_pk_bf16_f32 v148, v136, v137
	v_cvt_pk_bf16_f32 v149, v138, v139
	v_cvt_pk_bf16_f32 v150, v140, v141
	v_cvt_pk_bf16_f32 v151, v142, v143
	v_add_u32_e32 v207, 0x3d000, v202
	global_store_short v207, v148, s[8:9] offset:-4096
	global_store_short_d16_hi v207, v148, s[8:9] offset:-2048
	global_store_short v207, v149, s[8:9] offset:0
	global_store_short_d16_hi v207, v149, s[8:9] offset:2048
	global_store_short v207, v150, s[8:9] offset:-4032
	global_store_short_d16_hi v207, v150, s[8:9] offset:-1984
	global_store_short v207, v151, s[8:9] offset:64
	global_store_short_d16_hi v207, v151, s[8:9] offset:2112
	s_load_dword s14, s[10:11], 0x0
	s_waitcnt lgkmcnt(0)
	s_add_i32 s28, s14, s28
	s_cmpk_lt_i32 s28, 0x100
	s_cbranch_scc0 .LBB0_1389
